# attention O stores write-through (sc1) on top of v12
# speedup vs baseline: 1.0489x; 1.0004x over previous
; __device__ __forceinline__ int crow(int r,int hi){return (r&3)+8*(r>>2)+4*hi;}
; template<int THRL> __device__ __forceinline__ void attn_unit(int b,int h,int qb,const bf16*Q,const bf16*__restrict__ K,const bf16*__restrict__ V,bf16*O,const bf16*__restrict__ Gt,const float*__restrict__ LOGF,const float qkbound,const int reuse,char*shm,const int tid_in){
;     ...
;   if(hi==0)wsf[32+r32]=l_reg;asm volatile("s_waitcnt lgkmcnt(0)":::"memory");
;   float rli[16];
;   #pragma unroll
;   for(int r=0;r<16;++r)rli[r]=__builtin_amdgcn_rcpf(wsf[32+crow(r,hi)]);
;   bf16*Ow=O+(rowbase+q0+wid*QBLK)*DM+h*D; const bf16*Gw=Gt+(rowbase+q0+wid*QBLK)*DM+h*D;
;   u32x4 gv[4];
;   #pragma unroll
;   for(int i=0;i<4;++i){const int row=i*8+(lane>>3),ch=lane&7; gv[i]=*(const u32x4*)(Gw+(long)row*DM+ch*8);}
;   { bf16*stg=(bf16*)(shm+LDS_OST)+wid*2048;
;     #pragma unroll
;     for(int r=0;r<16;++r){const int orow=crow(r,hi);
;       #pragma unroll
;       for(int d0=0;d0<2;++d0)stg[orow*64+d0*32+r32]=__float2bfloat16(o[d0][r]*rli[r]);}
;     asm volatile("s_waitcnt lgkmcnt(0)":::"memory");
;     #pragma unroll
;     for(int i=0;i<4;++i){const int row=i*8+(lane>>3),ch=lane&7; u32x4 v=*(const u32x4*)(stg+row*64+ch*8);
.LBB0_330:
	s_or_b64 exec, exec, s[4:5]
	s_waitcnt lgkmcnt(0)
	ds_read_b128 v[32:35], v64 offset:49280
	ds_read_b128 v[36:39], v64 offset:49312
	s_lshl_b64 s[4:5], s[20:21], 1
	s_add_u32 s4, s60, s4
	s_addc_u32 s5, s61, s5
	s_waitcnt lgkmcnt(1)
	v_rcp_f32_e32 v48, v32
	v_rcp_f32_e32 v49, v33
	v_rcp_f32_e32 v50, v34
	v_rcp_f32_e32 v51, v35
	ds_read_b128 v[32:35], v64 offset:49344
	s_lshl_b64 s[0:1], s[0:1], 1
	s_add_u32 s0, s4, s0
	s_addc_u32 s1, s5, s1
	s_add_u32 s0, s0, s8
	s_addc_u32 s1, s1, s9
	v_mov_b32_e32 v209, v115
	s_waitcnt lgkmcnt(1)
	v_rcp_f32_e32 v52, v36
	v_rcp_f32_e32 v53, v37
	v_rcp_f32_e32 v54, v38
	v_rcp_f32_e32 v55, v39
	ds_read_b128 v[36:39], v64 offset:49376
	s_waitcnt lgkmcnt(1)
	v_rcp_f32_e32 v56, v32
	v_rcp_f32_e32 v57, v33
	v_lshl_add_u64 v[32:33], s[0:1], 0, v[208:209]
	v_mov_b32_e32 v211, v115
	v_lshl_add_u64 v[32:33], v[32:33], 0, v[210:211]
	s_movk_i32 s0, 0x4000
	v_rcp_f32_e32 v58, v34
	v_add_co_u32_e32 v34, vcc, s0, v32
	v_rcp_f32_e32 v59, v35
	s_nop 0
	v_addc_co_u32_e32 v35, vcc, 0, v33, vcc
	global_load_dwordx4 v[44:47], v[32:33], off
	global_load_dwordx4 v[40:43], v[34:35], off
	s_mov_b32 s0, 0x8000
	v_add_co_u32_e32 v34, vcc, s0, v32
	s_mov_b32 s0, 0xc000
	s_nop 0
	v_addc_co_u32_e32 v35, vcc, 0, v33, vcc
	v_add_co_u32_e32 v32, vcc, s0, v32
	s_lshl_b32 s0, s73, 12
	s_add_i32 s0, s0, 0
	v_lshlrev_b32_e32 v64, 1, v239
	v_mul_f32_e32 v0, v0, v48
	v_addc_co_u32_e32 v33, vcc, 0, v33, vcc
	v_add3_u32 v64, s0, v64, v231
	v_cvt_pk_bf16_f32 v0, v0, s0
	s_waitcnt lgkmcnt(0)
	v_rcp_f32_e32 v60, v36
	v_rcp_f32_e32 v61, v37
	v_rcp_f32_e32 v62, v38
	v_rcp_f32_e32 v63, v39
	global_load_dwordx4 v[36:39], v[34:35], off
	s_nop 0
	global_load_dwordx4 v[32:35], v[32:33], off
	ds_write_b16 v64, v0 offset:51264
	v_mul_f32_e32 v0, v17, v49
	v_cvt_pk_bf16_f32 v0, v0, s0
	ds_write_b16 v64, v0 offset:51328
	v_mul_f32_e32 v0, v1, v49
	v_cvt_pk_bf16_f32 v0, v0, s0
	ds_write_b16 v64, v0 offset:51392
	v_mul_f32_e32 v0, v18, v50
	v_cvt_pk_bf16_f32 v0, v0, s0
	ds_write_b16 v64, v0 offset:51456
	v_mul_f32_e32 v0, v2, v50
	v_cvt_pk_bf16_f32 v0, v0, s0
	ds_write_b16 v64, v0 offset:51520
	v_mul_f32_e32 v0, v19, v51
	v_cvt_pk_bf16_f32 v0, v0, s0
	ds_write_b16 v64, v0 offset:51584
	v_mul_f32_e32 v0, v3, v51
	v_cvt_pk_bf16_f32 v0, v0, s0
	ds_write_b16 v64, v0 offset:51648
	v_mul_f32_e32 v0, v20, v52
	v_cvt_pk_bf16_f32 v0, v0, s0
	ds_write_b16 v64, v0 offset:52224
	v_mul_f32_e32 v0, v4, v52
	v_cvt_pk_bf16_f32 v0, v0, s0
	ds_write_b16 v64, v0 offset:52288
	v_mul_f32_e32 v0, v21, v53
	v_cvt_pk_bf16_f32 v0, v0, s0
	ds_write_b16 v64, v0 offset:52352
	v_mul_f32_e32 v0, v5, v53
	v_cvt_pk_bf16_f32 v0, v0, s0
	ds_write_b16 v64, v0 offset:52416
	v_mul_f32_e32 v0, v22, v54
	v_cvt_pk_bf16_f32 v0, v0, s0
	ds_write_b16 v64, v0 offset:52480
	v_mul_f32_e32 v0, v6, v54
	v_cvt_pk_bf16_f32 v0, v0, s0
	ds_write_b16 v64, v0 offset:52544
	v_mul_f32_e32 v0, v23, v55
	v_cvt_pk_bf16_f32 v0, v0, s0
	ds_write_b16 v64, v0 offset:52608
	v_mul_f32_e32 v0, v7, v55
	v_cvt_pk_bf16_f32 v0, v0, s0
	ds_write_b16 v64, v0 offset:52672
	v_mul_f32_e32 v0, v24, v56
	v_cvt_pk_bf16_f32 v0, v0, s0
	ds_write_b16 v64, v0 offset:53248
	v_mul_f32_e32 v0, v8, v56
	v_cvt_pk_bf16_f32 v0, v0, s0
	ds_write_b16 v64, v0 offset:53312
	v_mul_f32_e32 v0, v25, v57
	v_cvt_pk_bf16_f32 v0, v0, s0
	ds_write_b16 v64, v0 offset:53376
	v_mul_f32_e32 v0, v9, v57
	v_cvt_pk_bf16_f32 v0, v0, s0
	ds_write_b16 v64, v0 offset:53440
	v_mul_f32_e32 v0, v26, v58
	v_cvt_pk_bf16_f32 v0, v0, s0
	ds_write_b16 v64, v0 offset:53504
	v_mul_f32_e32 v0, v10, v58
	v_cvt_pk_bf16_f32 v0, v0, s0
	ds_write_b16 v64, v0 offset:53568
	v_mul_f32_e32 v0, v27, v59
	v_cvt_pk_bf16_f32 v0, v0, s0
	ds_write_b16 v64, v0 offset:53632
	v_mul_f32_e32 v0, v11, v59
	v_cvt_pk_bf16_f32 v0, v0, s0
	ds_write_b16 v64, v0 offset:53696
	v_mul_f32_e32 v0, v28, v60
	v_cvt_pk_bf16_f32 v0, v0, s0
	ds_write_b16 v64, v0 offset:54272
	v_mul_f32_e32 v0, v12, v60
	v_cvt_pk_bf16_f32 v0, v0, s0
	ds_write_b16 v64, v0 offset:54336
	v_mul_f32_e32 v0, v29, v61
	v_cvt_pk_bf16_f32 v0, v0, s0
	ds_write_b16 v64, v0 offset:54400
	v_mul_f32_e32 v0, v13, v61
	v_cvt_pk_bf16_f32 v0, v0, s0
	ds_write_b16 v64, v0 offset:54464
	v_mul_f32_e32 v0, v30, v62
	v_cvt_pk_bf16_f32 v0, v0, s0
	ds_write_b16 v64, v0 offset:54528
	v_mul_f32_e32 v0, v14, v62
	v_cvt_pk_bf16_f32 v0, v0, s0
	ds_write_b16 v64, v0 offset:54592
	v_mul_f32_e32 v0, v31, v63
	v_cvt_pk_bf16_f32 v0, v0, s0
	v_mul_f32_e32 v16, v16, v48
	ds_write_b16 v64, v0 offset:54656
	v_mul_f32_e32 v0, v15, v63
	s_waitcnt vmcnt(3)
	v_lshlrev_b32_e32 v3, 16, v44
	v_cvt_pk_bf16_f32 v16, v16, s0
	v_cvt_pk_bf16_f32 v0, v0, s0
	v_and_b32_e32 v4, 0xffff0000, v44
	v_mul_f32_e32 v3, 0xbfb8aa3b, v3
	ds_write_b16 v64, v16 offset:51200
	ds_write_b16 v64, v0 offset:54720
	v_add_u32_e32 v14, s0, v208
	v_exp_f32_e32 v6, v3
	v_mul_f32_e32 v3, 0xbfb8aa3b, v4
	s_waitcnt lgkmcnt(0)
	v_add_u32_e32 v2, v14, v234
	v_exp_f32_e32 v7, v3
	ds_read_b128 v[2:5], v2 offset:51200
	v_add_f32_e32 v6, 1.0, v6
	v_rcp_f32_e32 v10, v6
	v_add_f32_e32 v6, 1.0, v7
	v_rcp_f32_e32 v11, v6
	v_add_u32_e32 v6, v14, v235
	ds_read_b128 v[6:9], v6 offset:51200
	s_waitcnt lgkmcnt(1)
; __device__ __forceinline__ unsigned cvtpk_s(float lo,float hi){f32x2_t v={lo,hi};bf16x2_t b=__builtin_convertvector(v,bf16x2_t);return __builtin_bit_cast(unsigned,b);}
; template<int THRL> __device__ __forceinline__ void attn_unit(int b,int h,int qb,const bf16*Q,const bf16*__restrict__ K,const bf16*__restrict__ V,bf16*O,const bf16*__restrict__ Gt,const float*__restrict__ LOGF,const float qkbound,const int reuse,char*shm,const int tid_in){
;     ...
;     for(int i=0;i<4;++i){const int row=i*8+(lane>>3),ch=lane&7; u32x4 v=*(const u32x4*)(stg+row*64+ch*8);
;       #pragma unroll
;       for(int w=0;w<4;++w){ const float olo=__uint_as_float(v[w]<<16), ohi=__uint_as_float(v[w]&0xffff0000u), glo=__uint_as_float(gv[i][w]<<16), ghi=__uint_as_float(gv[i][w]&0xffff0000u);
;         const float slo=__builtin_amdgcn_rcpf(1.0f+__builtin_amdgcn_exp2f(-1.4426950408889634f*glo)), shi=__builtin_amdgcn_rcpf(1.0f+__builtin_amdgcn_exp2f(-1.4426950408889634f*ghi));
;         v[w]=cvtpk_s(olo*slo,ohi*shi); }
;       ATTN_STORE16(Ow+(long)row*DM+ch*8,v);} }
	v_lshlrev_b32_e32 v12, 16, v2
	v_and_b32_e32 v13, 0xffff0000, v2
	v_lshlrev_b32_e32 v2, 16, v45
	v_and_b32_e32 v15, 0xffff0000, v45
	v_mul_f32_e32 v2, 0xbfb8aa3b, v2
	v_exp_f32_e32 v2, v2
	v_mul_f32_e32 v15, 0xbfb8aa3b, v15
	v_exp_f32_e32 v15, v15
	v_pk_mul_f32 v[10:11], v[10:11], v[12:13]
	v_add_f32_e32 v2, 1.0, v2
	v_rcp_f32_e32 v12, v2
	v_add_f32_e32 v2, 1.0, v15
	v_rcp_f32_e32 v13, v2
	v_cvt_pk_bf16_f32 v2, v10, v11
	v_lshlrev_b32_e32 v10, 16, v3
	v_and_b32_e32 v11, 0xffff0000, v3
	v_lshlrev_b32_e32 v3, 16, v46
	v_pk_mul_f32 v[10:11], v[12:13], v[10:11]
	v_and_b32_e32 v12, 0xffff0000, v46
	v_mul_f32_e32 v3, 0xbfb8aa3b, v3
	v_exp_f32_e32 v13, v3
	v_mul_f32_e32 v3, 0xbfb8aa3b, v12
	v_exp_f32_e32 v12, v3
	v_cvt_pk_bf16_f32 v3, v10, v11
	v_add_f32_e32 v10, 1.0, v13
	v_and_b32_e32 v13, 0xffff0000, v4
	v_add_f32_e32 v11, 1.0, v12
	v_lshlrev_b32_e32 v12, 16, v4
	v_lshlrev_b32_e32 v4, 16, v47
	v_and_b32_e32 v15, 0xffff0000, v47
	v_mul_f32_e32 v4, 0xbfb8aa3b, v4
	v_exp_f32_e32 v4, v4
	v_mul_f32_e32 v15, 0xbfb8aa3b, v15
	v_rcp_f32_e32 v10, v10
	v_rcp_f32_e32 v11, v11
	v_exp_f32_e32 v15, v15
	v_add_f32_e32 v4, 1.0, v4
	v_lshl_add_u64 v[0:1], s[6:7], 0, v[208:209]
	v_pk_mul_f32 v[10:11], v[10:11], v[12:13]
	v_rcp_f32_e32 v12, v4
	v_add_f32_e32 v4, 1.0, v15
	v_rcp_f32_e32 v13, v4
	v_cvt_pk_bf16_f32 v4, v10, v11
	v_lshlrev_b32_e32 v10, 16, v5
	v_and_b32_e32 v11, 0xffff0000, v5
	v_pk_mul_f32 v[10:11], v[12:13], v[10:11]
	s_waitcnt vmcnt(2)
	v_lshlrev_b32_e32 v12, 16, v40
	v_and_b32_e32 v13, 0xffff0000, v40
	v_mul_f32_e32 v12, 0xbfb8aa3b, v12
	v_mul_f32_e32 v13, 0xbfb8aa3b, v13
	v_exp_f32_e32 v12, v12
	v_exp_f32_e32 v13, v13
	v_mov_b32_e32 v213, v115
	v_cvt_pk_bf16_f32 v5, v10, v11
	v_lshl_add_u64 v[10:11], v[0:1], 0, v[212:213]
	global_store_dwordx4 v[10:11], v[2:5], off sc1
	v_and_b32_e32 v10, 0xffff0000, v41
	v_mul_f32_e32 v10, 0xbfb8aa3b, v10
	s_waitcnt lgkmcnt(0)
	v_lshlrev_b32_e32 v4, 16, v6
	v_and_b32_e32 v5, 0xffff0000, v6
	v_lshlrev_b32_e32 v6, 16, v41
	v_add_f32_e32 v2, 1.0, v12
	v_add_f32_e32 v3, 1.0, v13
	v_mul_f32_e32 v6, 0xbfb8aa3b, v6
	v_rcp_f32_e32 v2, v2
	v_rcp_f32_e32 v3, v3
	v_exp_f32_e32 v6, v6
	v_exp_f32_e32 v10, v10
	v_mov_b32_e32 v215, v115
	v_pk_mul_f32 v[2:3], v[2:3], v[4:5]
	v_add_f32_e32 v4, 1.0, v6
	v_add_f32_e32 v5, 1.0, v10
	v_rcp_f32_e32 v4, v4
	v_rcp_f32_e32 v5, v5
	v_cvt_pk_bf16_f32 v2, v2, v3
	v_lshlrev_b32_e32 v6, 16, v7
	v_and_b32_e32 v7, 0xffff0000, v7
	v_lshlrev_b32_e32 v3, 16, v42
	v_pk_mul_f32 v[4:5], v[4:5], v[6:7]
	v_and_b32_e32 v6, 0xffff0000, v42
	v_mul_f32_e32 v3, 0xbfb8aa3b, v3
	v_exp_f32_e32 v7, v3
	v_mul_f32_e32 v3, 0xbfb8aa3b, v6
	v_exp_f32_e32 v6, v3
	v_cvt_pk_bf16_f32 v3, v4, v5
	v_add_f32_e32 v4, 1.0, v7
	v_and_b32_e32 v7, 0xffff0000, v8
	v_add_f32_e32 v5, 1.0, v6
	v_lshlrev_b32_e32 v6, 16, v8
	v_lshlrev_b32_e32 v8, 16, v43
	v_and_b32_e32 v10, 0xffff0000, v43
	v_mul_f32_e32 v8, 0xbfb8aa3b, v8
	v_mul_f32_e32 v10, 0xbfb8aa3b, v10
	v_rcp_f32_e32 v4, v4
	v_rcp_f32_e32 v5, v5
	v_exp_f32_e32 v8, v8
	v_exp_f32_e32 v10, v10
	v_mov_b32_e32 v217, v115
	v_pk_mul_f32 v[4:5], v[4:5], v[6:7]
	v_add_f32_e32 v6, 1.0, v8
	v_add_f32_e32 v7, 1.0, v10
	v_rcp_f32_e32 v6, v6
	v_rcp_f32_e32 v7, v7
	v_lshlrev_b32_e32 v8, 16, v9
	v_and_b32_e32 v9, 0xffff0000, v9
	v_cvt_pk_bf16_f32 v4, v4, v5
	v_pk_mul_f32 v[6:7], v[6:7], v[8:9]
	v_mov_b32_e32 v219, v115
	v_cvt_pk_bf16_f32 v5, v6, v7
	v_lshl_add_u64 v[6:7], v[0:1], 0, v[214:215]
	global_store_dwordx4 v[6:7], v[2:5], off sc1
	s_add_i32 s66, s66, 1
	s_mov_b64 s[0:1], 0
	s_waitcnt vmcnt(3)
; __device__ __forceinline__ unsigned cvtpk_s(float lo,float hi){f32x2_t v={lo,hi};bf16x2_t b=__builtin_convertvector(v,bf16x2_t);return __builtin_bit_cast(unsigned,b);}
; template<int THRL> __device__ __forceinline__ void attn_unit(int b,int h,int qb,const bf16*Q,const bf16*__restrict__ K,const bf16*__restrict__ V,bf16*O,const bf16*__restrict__ Gt,const float*__restrict__ LOGF,const float qkbound,const int reuse,char*shm,const int tid_in){
;     ...
;     for(int i=0;i<4;++i){const int row=i*8+(lane>>3),ch=lane&7; u32x4 v=*(const u32x4*)(stg+row*64+ch*8);
;       #pragma unroll
;       for(int w=0;w<4;++w){ const float olo=__uint_as_float(v[w]<<16), ohi=__uint_as_float(v[w]&0xffff0000u), glo=__uint_as_float(gv[i][w]<<16), ghi=__uint_as_float(gv[i][w]&0xffff0000u);
;         const float slo=__builtin_amdgcn_rcpf(1.0f+__builtin_amdgcn_exp2f(-1.4426950408889634f*glo)), shi=__builtin_amdgcn_rcpf(1.0f+__builtin_amdgcn_exp2f(-1.4426950408889634f*ghi));
;         v[w]=cvtpk_s(olo*slo,ohi*shi); }
;       ATTN_STORE16(Ow+(long)row*DM+ch*8,v);} }
;   asm volatile("s_waitcnt lgkmcnt(0)\n\ts_barrier":::"memory");
	v_lshlrev_b32_e32 v3, 16, v36
	v_and_b32_e32 v4, 0xffff0000, v36
	v_mul_f32_e32 v3, 0xbfb8aa3b, v3
	v_exp_f32_e32 v6, v3
	v_mul_f32_e32 v3, 0xbfb8aa3b, v4
	v_add_u32_e32 v2, v14, v196
	v_exp_f32_e32 v7, v3
	ds_read_b128 v[2:5], v2 offset:51200
	v_add_f32_e32 v6, 1.0, v6
	v_rcp_f32_e32 v10, v6
	v_add_f32_e32 v6, 1.0, v7
	v_rcp_f32_e32 v11, v6
	v_add_u32_e32 v6, v14, v197
	ds_read_b128 v[6:9], v6 offset:51200
	s_waitcnt lgkmcnt(1)
	v_lshlrev_b32_e32 v12, 16, v2
	v_and_b32_e32 v13, 0xffff0000, v2
	v_lshlrev_b32_e32 v2, 16, v37
	v_and_b32_e32 v14, 0xffff0000, v37
	v_mul_f32_e32 v2, 0xbfb8aa3b, v2
	v_exp_f32_e32 v2, v2
	v_mul_f32_e32 v14, 0xbfb8aa3b, v14
	v_exp_f32_e32 v14, v14
	v_pk_mul_f32 v[10:11], v[10:11], v[12:13]
	v_add_f32_e32 v2, 1.0, v2
	v_rcp_f32_e32 v12, v2
	v_add_f32_e32 v2, 1.0, v14
	v_rcp_f32_e32 v13, v2
	v_cvt_pk_bf16_f32 v2, v10, v11
	v_lshlrev_b32_e32 v10, 16, v3
	v_and_b32_e32 v11, 0xffff0000, v3
	v_lshlrev_b32_e32 v3, 16, v38
	v_pk_mul_f32 v[10:11], v[12:13], v[10:11]
	v_and_b32_e32 v12, 0xffff0000, v38
	v_mul_f32_e32 v3, 0xbfb8aa3b, v3
	v_exp_f32_e32 v13, v3
	v_mul_f32_e32 v3, 0xbfb8aa3b, v12
	v_exp_f32_e32 v12, v3
	v_cvt_pk_bf16_f32 v3, v10, v11
	v_add_f32_e32 v10, 1.0, v13
	v_and_b32_e32 v13, 0xffff0000, v4
	v_add_f32_e32 v11, 1.0, v12
	v_lshlrev_b32_e32 v12, 16, v4
	v_lshlrev_b32_e32 v4, 16, v39
	v_and_b32_e32 v14, 0xffff0000, v39
	v_mul_f32_e32 v4, 0xbfb8aa3b, v4
	v_exp_f32_e32 v4, v4
	v_mul_f32_e32 v14, 0xbfb8aa3b, v14
	v_rcp_f32_e32 v10, v10
	v_rcp_f32_e32 v11, v11
	v_exp_f32_e32 v14, v14
	v_add_f32_e32 v4, 1.0, v4
	v_pk_mul_f32 v[10:11], v[10:11], v[12:13]
	v_rcp_f32_e32 v12, v4
	v_add_f32_e32 v4, 1.0, v14
	v_rcp_f32_e32 v13, v4
	v_cvt_pk_bf16_f32 v4, v10, v11
	v_lshlrev_b32_e32 v10, 16, v5
	v_and_b32_e32 v11, 0xffff0000, v5
	v_pk_mul_f32 v[10:11], v[12:13], v[10:11]
	s_waitcnt vmcnt(2)
	v_lshlrev_b32_e32 v12, 16, v32
	v_and_b32_e32 v13, 0xffff0000, v32
	v_mul_f32_e32 v12, 0xbfb8aa3b, v12
	v_mul_f32_e32 v13, 0xbfb8aa3b, v13
	v_exp_f32_e32 v12, v12
	v_exp_f32_e32 v13, v13
	v_cvt_pk_bf16_f32 v5, v10, v11
	v_lshl_add_u64 v[10:11], v[0:1], 0, v[216:217]
	global_store_dwordx4 v[10:11], v[2:5], off sc1
	v_and_b32_e32 v10, 0xffff0000, v33
	v_mul_f32_e32 v10, 0xbfb8aa3b, v10
	s_waitcnt lgkmcnt(0)
	v_lshlrev_b32_e32 v4, 16, v6
	v_and_b32_e32 v5, 0xffff0000, v6
	v_lshlrev_b32_e32 v6, 16, v33
	v_add_f32_e32 v2, 1.0, v12
	v_add_f32_e32 v3, 1.0, v13
	v_mul_f32_e32 v6, 0xbfb8aa3b, v6
	v_rcp_f32_e32 v2, v2
	v_rcp_f32_e32 v3, v3
	v_exp_f32_e32 v6, v6
	v_exp_f32_e32 v10, v10
	v_lshl_add_u64 v[0:1], v[0:1], 0, v[218:219]
	v_pk_mul_f32 v[2:3], v[2:3], v[4:5]
	v_add_f32_e32 v4, 1.0, v6
	v_add_f32_e32 v5, 1.0, v10
	v_rcp_f32_e32 v4, v4
	v_rcp_f32_e32 v5, v5
	v_cvt_pk_bf16_f32 v2, v2, v3
	v_lshlrev_b32_e32 v6, 16, v7
	v_and_b32_e32 v7, 0xffff0000, v7
	v_lshlrev_b32_e32 v3, 16, v34
	v_pk_mul_f32 v[4:5], v[4:5], v[6:7]
	v_and_b32_e32 v6, 0xffff0000, v34
	v_mul_f32_e32 v3, 0xbfb8aa3b, v3
	v_exp_f32_e32 v7, v3
	v_mul_f32_e32 v3, 0xbfb8aa3b, v6
	v_exp_f32_e32 v6, v3
	v_cvt_pk_bf16_f32 v3, v4, v5
	v_add_f32_e32 v4, 1.0, v7
	v_and_b32_e32 v7, 0xffff0000, v8
	v_add_f32_e32 v5, 1.0, v6
	v_lshlrev_b32_e32 v6, 16, v8
	v_lshlrev_b32_e32 v8, 16, v35
	v_and_b32_e32 v10, 0xffff0000, v35
	v_mul_f32_e32 v8, 0xbfb8aa3b, v8
	v_mul_f32_e32 v10, 0xbfb8aa3b, v10
	v_rcp_f32_e32 v4, v4
	v_rcp_f32_e32 v5, v5
	v_exp_f32_e32 v8, v8
	v_exp_f32_e32 v10, v10
	v_pk_mul_f32 v[4:5], v[4:5], v[6:7]
	v_add_f32_e32 v6, 1.0, v8
	v_add_f32_e32 v7, 1.0, v10
	v_rcp_f32_e32 v6, v6
	v_rcp_f32_e32 v7, v7
	v_lshlrev_b32_e32 v8, 16, v9
	v_and_b32_e32 v9, 0xffff0000, v9
	v_cvt_pk_bf16_f32 v4, v4, v5
	v_pk_mul_f32 v[6:7], v[6:7], v[8:9]
	s_nop 0
	v_cvt_pk_bf16_f32 v5, v6, v7
	global_store_dwordx4 v[0:1], v[2:5], off sc1
	s_waitcnt lgkmcnt(0)
	s_barrier
